# prep_item prefetch v2: lb table prefetched with the P loads at item top, counted vmcnt(7) so the top never waits on recent stores
# speedup vs baseline: 1.0145x; 1.0034x over previous
; #define LAS __attribute__((address_space(3)))
; __device__ __forceinline__ size_t PIX(int row, int col) { return (size_t)(col >> 7) * PSLOT + (size_t)row * 128 + (col & 127); }
; __device__ void prep_item(const Params& p, int l, int item, LAS unsigned char* lds) {
;     ...
;     const int ci = item % NCH, bh = item / NCH, h = bh & 3, b = bh >> 2;
;     const int R0 = ci < 8 ? NLAT + b * 256 + 32 * ci : b * 4096 + 32 * (ci - 8);
;     bf16_t* P = (bf16_t*)(p.ws + WS_BIG);
;     const bool first = (l == 0);
;     const bool want_out = first || ci >= 8;
;     for (int dd = 0; dd < 2; ++dd) { LAS unsigned* az = (LAS unsigned*)(lds + dd * P1_DIRSZ + P1_AW) + w * (32 * KT_ST / 2); for (int i = lane; i < 32 * KT_ST / 2; i += 64) az[i] = 0u; }
;     u32x4 rf0, rq0, rv0, rf1, rq1, rv1;
;     { const int r_ = R0 + tau; rf0 = *(const u32x4*)(P + PIX(r_, h * 128 + k0)); rq0 = *(const u32x4*)(P + PIX(r_, 1536 + h * 128 + k0)); rv0 = *(const u32x4*)(P + PIX(r_, 1024 + h * 128 + k0)); }
;     { const int r_ = R0 + 31 - tau; rf1 = *(const u32x4*)(P + PIX(r_, 512 + h * 128 + k0)); rq1 = *(const u32x4*)(P + PIX(r_, 1536 + h * 128 + k0)); rv1 = *(const u32x4*)(P + PIX(r_, 1024 + h * 128 + k0)); }
;     asm volatile("s_waitcnt vmcnt(0)" ::: "memory");
;     __syncthreads();
;     auto valu_part = [&](const int dir, const u32x4& f, const u32x4& q, const u32x4& v) {
;         LAS unsigned char* db = lds + dir * P1_DIRSZ;
;         LAS bf16_t* Qs = (LAS bf16_t*)(db + P1_QS); LAS bf16_t* Kh = (LAS bf16_t*)(db + P1_KH);
;         LAS bf16_t* Vt = (LAS bf16_t*)(db + P1_VT); LAS bf16_t* Kt = (LAS bf16_t*)(db + P1_KT);
;         LAS bf16_t* Aw = (LAS bf16_t*)(db + P1_AW) + w * 32 * KT_ST;
;         const int tokl = dir ? 31 - tau : tau;
;         const float* lbp = (const float*)(p.ws + WS_LB) + dir * 512 + h * 128 + k0;
.Lpf_join_a:
	s_add_i32 s101, s101, s99
	s_mul_i32 s32, s100, 0x880000
	s_lshl_b32 s11, s101, 8
	s_add_u32 s32, s32, s11
	s_lshl_b32 s22, s100, 9
	s_add_u32 s18, s82, s32
	s_addc_u32 s19, s83, 0
	s_add_u32 s20, s18, 0x2200000
	s_addc_u32 s21, s19, 0
	s_add_u32 s98, s18, 0x4400000
	s_addc_u32 s99, s19, 0
	s_add_u32 s100, s18, 0x6600000
	s_addc_u32 s101, s19, 0
	global_load_dwordx4 v[188:191], v212, s[18:19]
	global_load_dwordx4 v[192:195], v212, s[100:101]
	global_load_dwordx4 v[196:199], v212, s[98:99]
	global_load_dwordx4 v[200:203], v213, s[20:21]
	global_load_dwordx4 v[204:207], v213, s[100:101]
	global_load_dwordx4 v[208:211], v213, s[98:99]
	s_add_u32 s18, s85, s22
	v_readlane_b32 s19, v243, 43
	s_nop 1
	s_addc_u32 s19, s19, 0
	s_nop 4
	global_load_dwordx4 v[216:219], v214, s[18:19]
	global_load_dwordx4 v[220:223], v214, s[18:19] offset:16
	global_load_dwordx4 v[224:227], v214, s[18:19] offset:2048
	global_load_dwordx4 v[228:231], v214, s[18:19] offset:2064
	s_waitcnt vmcnt(0)
	s_branch .LBB0_243

; #define LAS __attribute__((address_space(3)))
; __device__ __forceinline__ size_t PIX(int row, int col) { return (size_t)(col >> 7) * PSLOT + (size_t)row * 128 + (col & 127); }
; __device__ __forceinline__ int opaque_tid() { int t = threadIdx.x; asm volatile("" : "+v"(t)); return t; }
; __device__ void prep_item(const Params& p, int l, int item, LAS unsigned char* lds) {
;     const int tid = opaque_tid(), w = tid >> 6, lane = tid & 63;
;     const int tau = lane & 31, kh = lane >> 5, k0 = 16 * w + 8 * kh, l15 = lane & 15, q4 = lane >> 4;
;     const int ci = item % NCH, bh = item / NCH, h = bh & 3, b = bh >> 2;
;     const int R0 = ci < 8 ? NLAT + b * 256 + 32 * ci : b * 4096 + 32 * (ci - 8);
;     bf16_t* P = (bf16_t*)(p.ws + WS_BIG);
;     const bool first = (l == 0);
;     const bool want_out = first || ci >= 8;
;     for (int dd = 0; dd < 2; ++dd) { LAS unsigned* az = (LAS unsigned*)(lds + dd * P1_DIRSZ + P1_AW) + w * (32 * KT_ST / 2); for (int i = lane; i < 32 * KT_ST / 2; i += 64) az[i] = 0u; }
;     u32x4 rf0, rq0, rv0, rf1, rq1, rv1;
;     { const int r_ = R0 + tau; rf0 = *(const u32x4*)(P + PIX(r_, h * 128 + k0)); rq0 = *(const u32x4*)(P + PIX(r_, 1536 + h * 128 + k0)); rv0 = *(const u32x4*)(P + PIX(r_, 1024 + h * 128 + k0)); }
;     { const int r_ = R0 + 31 - tau; rf1 = *(const u32x4*)(P + PIX(r_, 512 + h * 128 + k0)); rq1 = *(const u32x4*)(P + PIX(r_, 1536 + h * 128 + k0)); rv1 = *(const u32x4*)(P + PIX(r_, 1024 + h * 128 + k0)); }
;     asm volatile("s_waitcnt vmcnt(0)" ::: "memory");
;     __syncthreads();
.LBB0_247:
	v_ashrrev_i32_e32 v1, 6, v54
	s_and_b32 s74, s6, 3
	v_lshlrev_b32_e32 v30, 4, v1
	s_lshl_b32 s6, s74, 7
	v_and_b32_e32 v31, 31, v54
	v_lshrrev_b32_e32 v0, 2, v54
	v_add_u32_e32 v3, s6, v30
	v_and_b32_e32 v0, 8, v0
	v_add_u32_e32 v2, s70, v31
	v_ashrrev_i32_e32 v4, 7, v3
	v_mov_b32_e32 v3, v8
	s_movk_i32 s0, 0x78
	v_mov_b64_e32 v[10:11], s[82:83]
	v_bitop3_b32 v6, v30, s0, v0 bitop3:0xc8
	v_mad_i64_i32 v[4:5], s[0:1], v4, s87, v[10:11]
	v_lshlrev_b64 v[36:37], 8, v[2:3]
	s_or_b32 s7, s6, 0x600
	v_lshl_add_u64 v[2:3], v[4:5], 0, v[36:37]
	v_add_u32_e32 v4, s7, v30
	v_ashrrev_i32_e32 v4, 7, v4
	v_lshlrev_b32_e32 v12, 1, v6
	v_mov_b32_e32 v13, v8
	v_mad_i64_i32 v[14:15], s[0:1], v4, s87, v[10:11]
	v_lshl_add_u64 v[2:3], v[2:3], 0, v[12:13]
	v_lshl_add_u64 v[4:5], v[14:15], 0, v[36:37]
	v_lshl_add_u64 v[16:17], v[4:5], 0, v[12:13]
	s_or_b32 s72, s6, 0x400
	s_or_b32 s71, s6, 0x200
	v_add_u32_e32 v2, s72, v30
	v_bitop3_b32 v56, v54, 31, v54 bitop3:0xc
	v_add_u32_e32 v9, s71, v30
	v_ashrrev_i32_e32 v2, 7, v2
	v_add_u32_e32 v18, s70, v56
	v_ashrrev_i32_e32 v9, 7, v9
	v_mov_b32_e32 v19, v8
	v_mad_i64_i32 v[2:3], s[0:1], v2, s87, v[10:11]
	v_mad_i64_i32 v[10:11], s[0:1], v9, s87, v[10:11]
	v_lshlrev_b64 v[32:33], 8, v[18:19]
	v_lshl_add_u64 v[16:17], v[2:3], 0, v[36:37]
	v_lshl_add_u64 v[10:11], v[10:11], 0, v[32:33]
	v_lshl_add_u64 v[16:17], v[16:17], 0, v[12:13]
	v_lshl_add_u64 v[10:11], v[10:11], 0, v[12:13]
	v_lshl_add_u64 v[10:11], v[14:15], 0, v[32:33]
	v_lshl_add_u64 v[10:11], v[10:11], 0, v[12:13]
	v_lshl_add_u64 v[2:3], v[2:3], 0, v[32:33]
	v_lshl_add_u64 v[2:3], v[2:3], 0, v[12:13]
	s_nop 0
	s_movk_i32 s0, 0xa00
	v_and_b32_e32 v57, 63, v54
	v_mul_lo_u32 v1, v1, s0
	v_readlane_b32 s1, v240, 18
	v_cndmask_b32_e64 v2, 0, 1, s[88:89]
	v_lshlrev_b32_e32 v3, 2, v57
	v_add_u32_e32 v55, 16, v1
	v_add_u32_e32 v9, s1, v1
	v_cmp_ne_u32_e64 s[40:41], 1, v2
	v_add_u32_e32 v1, v55, v3
	v_add_u32_e32 v2, v9, v3
	ds_write2st64_b32 v1, v8, v8 offset0:148 offset1:149
	ds_write2st64_b32 v1, v8, v8 offset0:150 offset1:151
	ds_write2st64_b32 v1, v8, v8 offset0:152 offset1:153
	ds_write2st64_b32 v1, v8, v8 offset0:154 offset1:155
	ds_write2st64_b32 v1, v8, v8 offset0:156 offset1:157
	ds_write2st64_b32 v2, v8, v8 offset1:1
	ds_write2st64_b32 v2, v8, v8 offset0:2 offset1:3
	ds_write2st64_b32 v2, v8, v8 offset0:4 offset1:5
	ds_write2st64_b32 v2, v8, v8 offset0:6 offset1:7
	ds_write2st64_b32 v2, v8, v8 offset0:8 offset1:9
	s_lshl_b32 s0, s74, 9
	s_waitcnt vmcnt(7)
	v_mov_b64_e32 v[156:157], v[216:217]
	v_mov_b64_e32 v[158:159], v[218:219]
	v_mov_b64_e32 v[160:161], v[220:221]
	v_mov_b64_e32 v[162:163], v[222:223]
	v_mov_b64_e32 v[168:169], v[224:225]
	v_mov_b64_e32 v[170:171], v[226:227]
	v_mov_b64_e32 v[172:173], v[228:229]
	v_mov_b64_e32 v[174:175], v[230:231]
	v_mov_b64_e32 v[4:5], v[188:189]
	v_mov_b64_e32 v[6:7], v[190:191]
	v_mov_b64_e32 v[26:27], v[192:193]
	v_mov_b64_e32 v[28:29], v[194:195]
	v_mov_b64_e32 v[22:23], v[196:197]
	v_mov_b64_e32 v[24:25], v[198:199]
	v_mov_b64_e32 v[18:19], v[200:201]
	v_mov_b64_e32 v[20:21], v[202:203]
	v_mov_b64_e32 v[14:15], v[204:205]
	v_mov_b64_e32 v[16:17], v[206:207]
	v_mov_b64_e32 v[10:11], v[208:209]
	v_mov_b64_e32 v[12:13], v[210:211]
	s_sub_i32 s98, s2, s46
	s_cmp_lt_i32 s98, 0
	s_cselect_b32 s98, s2, s98
	s_mul_hi_u32 s99, s98, 0xf0f0f0f1
	s_lshr_b32 s100, s99, 7
	s_mul_i32 s101, s100, 0x88
	s_sub_i32 s98, s98, s101
	s_lshr_b32 s99, s99, 9
	s_and_b32 s100, s100, 3
	s_lshl_b32 s101, s98, 5
	s_cmp_gt_u32 s98, 7
	s_cbranch_scc1 .Lpf_lat_b
	s_lshl_b32 s99, s99, 8
	s_add_i32 s101, s101, 0x8000
	s_branch .Lpf_join_b

; #define LAS __attribute__((address_space(3)))
; __device__ __forceinline__ size_t PIX(int row, int col) { return (size_t)(col >> 7) * PSLOT + (size_t)row * 128 + (col & 127); }
; __device__ __forceinline__ float bf_lo(unsigned u) { return __uint_as_float(u << 16); }
; __device__ __forceinline__ float bf_hi(unsigned u) { return __uint_as_float(u & 0xffff0000u); }
; __device__ __forceinline__ float fast_rcp(float x) { return __builtin_amdgcn_rcpf(x); }
; __device__ void prep_item(const Params& p, int l, int item, LAS unsigned char* lds) {
;     ...
;     { const int r_ = R0 + tau; rf0 = *(const u32x4*)(P + PIX(r_, h * 128 + k0)); rq0 = *(const u32x4*)(P + PIX(r_, 1536 + h * 128 + k0)); rv0 = *(const u32x4*)(P + PIX(r_, 1024 + h * 128 + k0)); }
;     { const int r_ = R0 + 31 - tau; rf1 = *(const u32x4*)(P + PIX(r_, 512 + h * 128 + k0)); rq1 = *(const u32x4*)(P + PIX(r_, 1536 + h * 128 + k0)); rv1 = *(const u32x4*)(P + PIX(r_, 1024 + h * 128 + k0)); }
;     asm volatile("s_waitcnt vmcnt(0)" ::: "memory");
;     __syncthreads();
;     auto valu_part = [&](const int dir, const u32x4& f, const u32x4& q, const u32x4& v) {
;         LAS unsigned char* db = lds + dir * P1_DIRSZ;
;         LAS bf16_t* Qs = (LAS bf16_t*)(db + P1_QS); LAS bf16_t* Kh = (LAS bf16_t*)(db + P1_KH);
;         LAS bf16_t* Vt = (LAS bf16_t*)(db + P1_VT); LAS bf16_t* Kt = (LAS bf16_t*)(db + P1_KT);
;         LAS bf16_t* Aw = (LAS bf16_t*)(db + P1_AW) + w * 32 * KT_ST;
;         const int tokl = dir ? 31 - tau : tau;
;         const float* lbp = (const float*)(p.ws + WS_LB) + dir * 512 + h * 128 + k0;
;         float E[8], kk[8];
; #pragma unroll
;         for (int j = 0; j < 8; ++j) {
;             const unsigned fw = f[j >> 1]; const float x = (j & 1) ? bf_hi(fw) : bf_lo(fw);
;             const float e = __expf(-fabsf(x)), r = fast_rcp(1.0f + e);
;             const float sp = x >= 0.f ? r : e * r, sn = x >= 0.f ? e * r : r;
;             if (first) { E[j] = sp; kk[j] = sn; }
;             else { const float lb = lbp[j]; const float gate = lb + (1.0f - lb) * sp; E[j] = gate; kk[j] = 1.0f - gate; }
.Lpf_join_b:
	s_add_i32 s101, s101, s99
	s_mul_i32 s32, s100, 0x880000
	s_lshl_b32 s11, s101, 8
	s_add_u32 s32, s32, s11
	s_lshl_b32 s22, s100, 9
	s_add_u32 s18, s82, s32
	s_addc_u32 s19, s83, 0
	s_add_u32 s20, s18, 0x2200000
	s_addc_u32 s21, s19, 0
	s_add_u32 s98, s18, 0x4400000
	s_addc_u32 s99, s19, 0
	s_add_u32 s100, s18, 0x6600000
	s_addc_u32 s101, s19, 0
	global_load_dwordx4 v[188:191], v212, s[18:19]
	global_load_dwordx4 v[192:195], v212, s[100:101]
	global_load_dwordx4 v[196:199], v212, s[98:99]
	global_load_dwordx4 v[200:203], v213, s[20:21]
	global_load_dwordx4 v[204:207], v213, s[100:101]
	global_load_dwordx4 v[208:211], v213, s[98:99]
	s_add_u32 s18, s85, s22
	v_readlane_b32 s19, v243, 43
	s_nop 1
	s_addc_u32 s19, s19, 0
	s_nop 4
	global_load_dwordx4 v[216:219], v214, s[18:19]
	global_load_dwordx4 v[220:223], v214, s[18:19] offset:16
	global_load_dwordx4 v[224:227], v214, s[18:19] offset:2048
	global_load_dwordx4 v[228:231], v214, s[18:19] offset:2064
	s_add_u32 s38, s85, s0
	v_readlane_b32 s0, v243, 43
	s_addc_u32 s39, s0, 0
	s_andn2_b64 vcc, exec, s[88:89]
	s_mov_b64 s[42:43], -1
	s_waitcnt lgkmcnt(0)
	s_barrier
	v_lshlrev_b32_e32 v2, 16, v4
	v_mul_f32_e64 v1, |v2|, s69
	v_exp_f32_e32 v3, v1
	v_cmp_le_f32_e64 s[0:1], 0, v2
	v_add_f32_e32 v1, 1.0, v3
	v_rcp_f32_e32 v1, v1
	s_nop 0
	v_mul_f32_e32 v2, v3, v1
	s_cbranch_vccnz .LBB0_249
	v_cndmask_b32_e64 v38, v1, v2, s[0:1]
	s_mov_b64 s[42:43], 0

; #define LAS __attribute__((address_space(3)))
; __device__ __forceinline__ size_t PIX(int row, int col) { return (size_t)(col >> 7) * PSLOT + (size_t)row * 128 + (col & 127); }
; __device__ __forceinline__ float bf_lo(unsigned u) { return __uint_as_float(u << 16); }
; __device__ void prep_item(const Params& p, int l, int item, LAS unsigned char* lds) {
;     ...
;         float qt[8], kh_[8], kt_[8], Tj[8];
;         cumprod32x8(E);
; #pragma unroll
;         for (int j = 0; j < 8; ++j) {
;             const float Ej = fmaxf(E[j], 1e-35f);
;             const float T0 = __builtin_bit_cast(float, __builtin_amdgcn_readlane(__builtin_bit_cast(int, Ej), 31)), T1 = __builtin_bit_cast(float, __builtin_amdgcn_readlane(__builtin_bit_cast(int, Ej), 63));
;             const float T = kh ? T1 : T0;
;             const unsigned qw = q[j >> 1]; const float qx = (j & 1) ? bf_hi(qw) : bf_lo(qw);
;             qt[j] = silu_f(qx) * 0.08838834764831845f * Ej;
;             kh_[j] = kk[j] * fast_rcp(Ej); kt_[j] = kh_[j] * T;
;             Tj[j] = T;
;         }
;         if (tau == 31) { float* dp = (float*)(p.ws + WS_DS) + ((size_t)((b * 4 + h) * 2 + dir) * NCH + ci) * 128 + k0;
;             *(f32x4*)dp = (f32x4){Tj[0], Tj[1], Tj[2], Tj[3]}; *(f32x4*)(dp + 4) = (f32x4){Tj[4], Tj[5], Tj[6], Tj[7]}; }
;         u32x4 wq, wk; wq.x = pk_bf16(qt[0], qt[1]); wq.y = pk_bf16(qt[2], qt[3]); wq.z = pk_bf16(qt[4], qt[5]); wq.w = pk_bf16(qt[6], qt[7]);
;         wk.x = pk_bf16(kh_[0], kh_[1]); wk.y = pk_bf16(kh_[2], kh_[3]); wk.z = pk_bf16(kh_[4], kh_[5]); wk.w = pk_bf16(kh_[6], kh_[7]);
;         *(LAS u32x4*)(Qs + tau * QS_ST + k0) = wq; *(LAS u32x4*)(Kh + tau * QS_ST + k0) = wk;
;         {
;           bf16_t* qd = (dir == 0) ? P + PIX(R0 + tokl, 1536 + h * 128) : (bf16_t*)(p.ws + WS_QB) + (size_t)h * PSLOT + (size_t)(R0 + tokl) * 128;
;           const int a32 = k0 & ~31, kkA = k0 & 31, kkB = kkA + 4;
;           u32x2 pa, pb; pa.x = wq.x; pa.y = wq.y; pb.x = wq.z; pb.y = wq.w;
;           *(u32x2*)(qd + a32 + 8 * ((kkA & 15) >> 2) + 4 * (kkA >> 4)) = pa;
;           *(u32x2*)(qd + a32 + 8 * ((kkB & 15) >> 2) + 4 * (kkB >> 4)) = pb; }
; #pragma unroll
;         for (int j = 0; j < 8; ++j) { Kt[(k0 + j) * KT_ST + tokl] = to_bf1(kt_[j]); const unsigned vw = v[j >> 1]; Vt[(k0 + j) * KT_ST + tau] = (bf16_t)((j & 1) ? (vw >> 16) : (vw & 0xffffu)); }
.LBB0_315:
	s_or_b64 exec, exec, s[0:1]
	v_lshlrev_b32_e32 v34, 16, v14
	v_and_b32_e32 v35, 0xffff0000, v14
	v_mul_f32_e32 v14, 0xbfb8aa3b, v34
	v_exp_f32_e32 v14, v14
	v_rcp_f32_e32 v50, v44
	v_rcp_f32_e32 v51, v45
	s_cmp_gt_u32 s73, 7
	v_add_f32_e32 v14, 1.0, v14
	v_rcp_f32_e32 v52, v14
	v_mul_f32_e32 v14, 0xbfb8aa3b, v35
	v_exp_f32_e32 v14, v14
	v_pk_mul_f32 v[22:23], v[22:23], v[50:51]
	v_readlane_b32 s6, v240, 28
	s_cselect_b64 s[0:1], -1, 0
	v_add_f32_e32 v14, 1.0, v14
	v_rcp_f32_e32 v53, v14
	v_rcp_f32_e32 v14, v42
	v_readlane_b32 s7, v240, 29
	v_mul_u32_u24_e32 v29, 0x110, v31
	v_pk_mul_f32 v[34:35], v[52:53], v[34:35]
	s_or_b64 s[6:7], s[6:7], s[0:1]
	v_pk_mul_f32 v[34:35], v[34:35], s[86:87] op_sel_hi:[1,0]
	v_readlane_b32 s0, v240, 19
	v_pk_mul_f32 v[34:35], v[34:35], v[44:45]
	v_lshlrev_b32_e32 v44, 16, v15
	v_and_b32_e32 v45, 0xffff0000, v15
	v_mul_f32_e32 v15, 0xbfb8aa3b, v44
	v_exp_f32_e32 v15, v15
	v_add3_u32 v29, s0, v29, v46
	s_mul_i32 s0, s74, 0x880000
	v_readlane_b32 s1, v242, 6
	v_add_f32_e32 v15, 1.0, v15
	v_rcp_f32_e32 v50, v15
	v_mul_f32_e32 v15, 0xbfb8aa3b, v45
	v_exp_f32_e32 v15, v15
	s_add_u32 s8, s1, s0
	v_readlane_b32 s1, v242, 7
	s_addc_u32 s9, s1, 0
	v_add_f32_e32 v15, 1.0, v15
	v_rcp_f32_e32 v51, v15
	v_rcp_f32_e32 v15, v43
	v_lshl_add_u64 v[32:33], s[8:9], 0, v[32:33]
	v_mov_b32_e32 v37, v8
	v_pk_mul_f32 v[44:45], v[50:51], v[44:45]
	v_readlane_b32 s1, v242, 60
	v_pk_mul_f32 v[44:45], v[44:45], s[86:87] op_sel_hi:[1,0]
	s_andn2_b64 vcc, exec, s[6:7]
	v_pk_mul_f32 v[44:45], v[44:45], v[42:43]
	v_pk_mul_f32 v[42:43], v[18:19], v[14:15]
	v_lshlrev_b32_e32 v18, 16, v16
	v_mul_f32_e32 v15, 0xbfb8aa3b, v18
	v_exp_f32_e32 v15, v15
	v_and_b32_e32 v19, 0xffff0000, v16
	v_rcp_f32_e32 v14, v40
	v_lshlrev_b32_e32 v16, 16, v17
	v_add_f32_e32 v15, 1.0, v15
	v_rcp_f32_e32 v50, v15
	v_mul_f32_e32 v15, 0xbfb8aa3b, v19
	v_exp_f32_e32 v15, v15
	v_and_b32_e32 v17, 0xffff0000, v17
	v_mul_f32_e32 v2, v42, v2
	v_mul_f32_e32 v3, v43, v3
	v_add_f32_e32 v15, 1.0, v15
	v_rcp_f32_e32 v51, v15
	v_rcp_f32_e32 v15, v41
	v_cvt_pk_bf16_f32 v2, v2, s0
	v_pk_mul_f32 v[18:19], v[50:51], v[18:19]
	v_pk_mul_f32 v[24:25], v[24:25], v[14:15]
	v_mul_f32_e32 v15, 0xbfb8aa3b, v16
	v_exp_f32_e32 v15, v15
	v_pk_mul_f32 v[18:19], v[18:19], s[86:87] op_sel_hi:[1,0]
	v_rcp_f32_e32 v14, v38
	v_pk_mul_f32 v[18:19], v[18:19], v[40:41]
	v_add_f32_e32 v15, 1.0, v15
	v_rcp_f32_e32 v40, v15
	v_mul_f32_e32 v15, 0xbfb8aa3b, v17
	v_exp_f32_e32 v15, v15
	v_cvt_pk_bf16_f32 v18, v18, v19
	v_mul_f32_e32 v4, v24, v4
	v_mul_f32_e32 v5, v25, v5
	v_add_f32_e32 v15, 1.0, v15
	v_rcp_f32_e32 v41, v15
	v_rcp_f32_e32 v15, v39
	v_pk_mul_f32 v[16:17], v[40:41], v[16:17]
	s_nop 0
	v_pk_mul_f32 v[16:17], v[16:17], s[86:87] op_sel_hi:[1,0]
	v_pk_mul_f32 v[20:21], v[20:21], v[14:15]
	v_pk_mul_f32 v[40:41], v[16:17], v[38:39]
	v_cvt_pk_bf16_f32 v38, v22, v23
	v_cvt_pk_bf16_f32 v19, v40, v41
	v_cvt_pk_bf16_f32 v39, v42, v43
	v_cvt_pk_bf16_f32 v40, v24, v25
	v_cvt_pk_bf16_f32 v41, v20, v21
	ds_write_b128 v29, v[38:41]
	v_mul_f32_e32 v7, v21, v7
	v_mul_f32_e32 v6, v20, v6
	v_mul_f32_e32 v20, v23, v1
	v_mul_f32_e32 v21, v22, v0
	v_lshl_add_u64 v[0:1], v[26:27], 1, v[32:33]
	v_mov_b32_e32 v29, v8
	v_lshl_add_u64 v[0:1], v[0:1], 0, v[28:29]
	v_cvt_pk_bf16_f32 v16, v34, v35
	v_cvt_pk_bf16_f32 v17, v44, v45
	v_lshl_add_u64 v[0:1], v[0:1], 0, v[36:37]
	ds_write_b128 v47, v[16:19] offset:58368
	global_store_dwordx2 v[0:1], v[16:17], off
	global_store_dwordx2 v[0:1], v[18:19], off offset:16
	v_lshlrev_b32_e32 v0, 1, v56
	v_lshlrev_b32_e32 v1, 1, v31
	v_cvt_pk_bf16_f32 v16, v21, s0
	v_add3_u32 v0, s1, v0, v48
	v_readlane_b32 s1, v240, 20
	ds_write_b16 v0, v16
	v_cvt_pk_bf16_f32 v16, v20, s0
	v_add3_u32 v1, s1, v1, v48
	ds_write_b16 v1, v10
	ds_write_b16 v0, v16 offset:80
	ds_write_b16_d16_hi v1, v10 offset:80
	ds_write_b16 v0, v2 offset:160
	ds_write_b16 v1, v11 offset:160
	v_cvt_pk_bf16_f32 v2, v3, s0
	ds_write_b16 v0, v2 offset:240
	ds_write_b16_d16_hi v1, v11 offset:240
	v_cvt_pk_bf16_f32 v2, v4, s0
	ds_write_b16 v0, v2 offset:320
	ds_write_b16 v1, v12 offset:320
	v_cvt_pk_bf16_f32 v2, v5, s0
	ds_write_b16 v0, v2 offset:400
	ds_write_b16_d16_hi v1, v12 offset:400
	v_cvt_pk_bf16_f32 v2, v6, s0
	v_and_b32_e32 v14, 15, v54
	v_lshrrev_b32_e32 v15, 4, v57
	ds_write_b16 v0, v2 offset:480
	ds_write_b16 v1, v13 offset:480
	v_cvt_pk_bf16_f32 v2, v7, s0
	ds_write_b16 v0, v2 offset:560
	ds_write_b16_d16_hi v1, v13 offset:560
	v_cndmask_b32_e64 v0, 0, 1, s[6:7]
	v_mul_u32_u24_e32 v1, 0x88, v14
	v_lshlrev_b32_e32 v18, 2, v15
	v_or_b32_e32 v2, v30, v14
	s_movk_i32 s1, 0x50
	v_cmp_ne_u32_e64 s[38:39], 1, v0
	v_lshlrev_b32_e32 v0, 3, v15
	v_lshlrev_b32_e32 v19, 4, v15
	v_lshlrev_b32_e32 v10, 1, v14
	v_mul_u32_u24_e32 v17, 0x140, v15
	v_and_b32_e32 v6, 48, v54
	v_mul_u32_u24_e32 v7, 0x50, v14
	v_ashrrev_i32_e32 v31, 31, v30
	v_lshlrev_b32_e32 v22, 1, v1
	v_cmp_gt_u32_e64 s[40:41], v14, v18
	v_or_b32_e32 v12, 1, v18
	v_or_b32_e32 v16, 2, v18
	v_or_b32_e32 v13, 3, v18
	v_mul_lo_u32 v11, v2, s1
	s_waitcnt lgkmcnt(0)
	s_barrier
; #define LAS __attribute__((address_space(3)))
; __device__ __forceinline__ unsigned pk_bf16(float a, float b) { f32x2 v = {a, b}; bf2_t r = __builtin_convertvector(v, bf2_t); return __builtin_bit_cast(unsigned, r); }
; __device__ __forceinline__ bf16_t to_bf1(float a) { return (bf16_t)(pk_bf16(a, 0.f) & 0xffffu); }
; __device__ void prep_item(const Params& p, int l, int item, LAS unsigned char* lds) {
;     ...
;         if (want_out) {
;             f32x4 a00 = (f32x4){0.f, 0.f, 0.f, 0.f}, a10 = a00, a11 = a00;
; #pragma unroll
;             for (int kb = 0; kb < 4; ++kb) {
;                 const bf16x8 qn0 = *(const LAS bf16x8*)(Qs + l15 * QS_ST + 32 * kb + 8 * q4), qn1 = *(const LAS bf16x8*)(Qs + (16 + l15) * QS_ST + 32 * kb + 8 * q4);
;                 const bf16x8 kh0 = *(const LAS bf16x8*)(Kh + l15 * QS_ST + 32 * kb + 8 * q4), kh1 = *(const LAS bf16x8*)(Kh + (16 + l15) * QS_ST + 32 * kb + 8 * q4);
;                 a00 = __builtin_amdgcn_mfma_f32_16x16x32_bf16(qn0, kh0, a00, 0, 0, 0);
;                 a10 = __builtin_amdgcn_mfma_f32_16x16x32_bf16(qn1, kh0, a10, 0, 0, 0);
;                 a11 = __builtin_amdgcn_mfma_f32_16x16x32_bf16(qn1, kh1, a11, 0, 0, 0);
;             }
; #pragma unroll
;             for (int i = 0; i < 4; ++i) { const int t = 4 * q4 + i; const bool keep = l15 <= t;
;                 Aw[t * KT_ST + l15] = to_bf1(keep ? a00[i] : 0.f);
;                 Aw[(16 + t) * KT_ST + l15] = to_bf1(a10[i]);
;                 Aw[(16 + t) * KT_ST + 16 + l15] = to_bf1(keep ? a11[i] : 0.f); }
;             asm volatile("s_waitcnt lgkmcnt(0)" ::: "memory");
;             const bf16x8 vf = *(const LAS bf16x8*)(Vt + (16 * w + l15) * KT_ST + 8 * q4);
;             bf16_t* OFB = (bf16_t*)(p.ws + WS_OFB) + (size_t)dir * NROW * 512;
; #pragma unroll
;             for (int mt = 0; mt < 2; ++mt) {
;                 const bf16x8 af = *(const LAS bf16x8*)(Aw + (16 * mt + l15) * KT_ST + 8 * q4);
;                 const f32x4 o = __builtin_amdgcn_mfma_f32_16x16x32_bf16(vf, af, (f32x4){0.f, 0.f, 0.f, 0.f}, 0, 0, 0);
;                 const int tl = 16 * mt + l15, tok = dir ? 31 - tl : tl;
;                 u32x2 wv; wv.x = pk_bf16(o[0], o[1]); wv.y = pk_bf16(o[2], o[3]);
;                 *(u32x2*)(OFB + (size_t)h * PSLOT + (size_t)(R0 + tok) * 128 + 16 * w + 4 * q4) = wv;
;             }
	s_cbranch_vccnz .LBB0_317
	v_add3_u32 v1, 16, v22, v19
	ds_read_b128 v[2:5], v1
	ds_read_b128 v[24:27], v1 offset:4352
	ds_read_b128 v[32:35], v1 offset:8704
	ds_read_b128 v[36:39], v1 offset:13056
	s_movk_i32 s1, 0x140
	v_cmp_gt_u32_e32 vcc, v14, v12
	v_add3_u32 v23, v55, v7, v6
	s_waitcnt lgkmcnt(1)
	v_mfma_f32_16x16x32_bf16 v[2:5], v[2:5], v[32:35], 0
	v_readlane_b32 s6, v242, 8
	v_readlane_b32 s7, v242, 9
	s_add_u32 s6, s6, s0
	v_mfma_f32_16x16x32_bf16 v[32:35], v[24:27], v[32:35], 0
	v_add_u32_e32 v28, s70, v14
	v_mov_b32_e32 v29, v8
	s_addc_u32 s7, s7, 0
	s_waitcnt lgkmcnt(0)
	v_mfma_f32_16x16x32_bf16 v[24:27], v[24:27], v[36:39], 0
	ds_read_b128 v[36:39], v1 offset:64
	ds_read_b128 v[40:43], v1 offset:4416
	ds_read_b128 v[44:47], v1 offset:8768
	ds_read_b128 v[48:51], v1 offset:13120
	s_waitcnt lgkmcnt(1)
	v_mfma_f32_16x16x32_bf16 v[2:5], v[36:39], v[44:47], v[2:5]
	v_mfma_f32_16x16x32_bf16 v[32:35], v[40:43], v[44:47], v[32:35]
	s_waitcnt lgkmcnt(0)
	v_mfma_f32_16x16x32_bf16 v[24:27], v[40:43], v[48:51], v[24:27]
	ds_read_b128 v[36:39], v1 offset:128
	ds_read_b128 v[40:43], v1 offset:4480
	ds_read_b128 v[44:47], v1 offset:8832
	ds_read_b128 v[48:51], v1 offset:13184
	s_waitcnt lgkmcnt(1)
	v_mfma_f32_16x16x32_bf16 v[2:5], v[36:39], v[44:47], v[2:5]
	v_mfma_f32_16x16x32_bf16 v[32:35], v[40:43], v[44:47], v[32:35]
	s_waitcnt lgkmcnt(0)
	v_mfma_f32_16x16x32_bf16 v[24:27], v[40:43], v[48:51], v[24:27]
	ds_read_b128 v[36:39], v1 offset:192
	ds_read_b128 v[40:43], v1 offset:4544
	ds_read_b128 v[44:47], v1 offset:8896
	ds_read_b128 v[48:51], v1 offset:13248
	v_add_u32_e32 v1, v55, v10
	v_mad_u32_u24 v20, v15, s1, v1
	s_waitcnt lgkmcnt(1)
	v_mfma_f32_16x16x32_bf16 v[2:5], v[36:39], v[44:47], v[2:5]
	s_movk_i32 s1, 0x50
	v_mfma_f32_16x16x32_bf16 v[32:35], v[40:43], v[44:47], v[32:35]
	s_nop 5
	v_cvt_pk_bf16_f32 v2, v2, s0
	v_cndmask_b32_e64 v2, v2, 0, s[40:41]
	ds_write_b16 v20, v2 offset:37888
	s_waitcnt lgkmcnt(1)
	v_mfma_f32_16x16x32_bf16 v[24:27], v[40:43], v[48:51], v[24:27]
	v_add3_u32 v20, v55, v17, v10
	v_cvt_pk_bf16_f32 v2, v32, s0
	ds_write_b16 v20, v2 offset:39168
	s_nop 4
	v_cvt_pk_bf16_f32 v2, v24, s0
	v_cndmask_b32_e64 v2, v2, 0, s[40:41]
	ds_write_b16 v20, v2 offset:39200
	v_cvt_pk_bf16_f32 v2, v3, s0
	v_cndmask_b32_e64 v2, v2, 0, vcc
	v_mul_u32_u24_e32 v3, 0x50, v12
	v_mad_u32_u24 v20, v12, s1, v1
	ds_write_b16 v20, v2 offset:37888
	v_cvt_pk_bf16_f32 v2, v33, s0
	v_add3_u32 v3, v55, v3, v10
	ds_write_b16 v3, v2 offset:39168
	v_cvt_pk_bf16_f32 v2, v25, s0
	v_cndmask_b32_e64 v2, v2, 0, vcc
	ds_write_b16 v3, v2 offset:39200
	v_cmp_gt_u32_e32 vcc, v14, v16
	v_cvt_pk_bf16_f32 v2, v4, s0
	v_mad_u32_u24 v3, v12, s1, s1
	v_cndmask_b32_e64 v2, v2, 0, vcc
	v_add_u32_e32 v4, v1, v3
	ds_write_b16 v4, v2 offset:37888
	v_cvt_pk_bf16_f32 v2, v34, s0
	v_add3_u32 v3, v55, v3, v10
	ds_write_b16 v3, v2 offset:39168
	v_cvt_pk_bf16_f32 v2, v26, s0
	v_cndmask_b32_e64 v2, v2, 0, vcc
	ds_write_b16 v3, v2 offset:39200
	v_cmp_gt_u32_e32 vcc, v14, v13
	v_cvt_pk_bf16_f32 v2, v5, s0
	v_mad_u32_u24 v3, v12, s1, v186
	v_cndmask_b32_e64 v2, v2, 0, vcc
	v_add_u32_e32 v1, v1, v3
	ds_write_b16 v1, v2 offset:37888
	v_cvt_pk_bf16_f32 v1, v35, s0
	v_add3_u32 v2, v55, v3, v10
	ds_write_b16 v2, v1 offset:39168
	v_cvt_pk_bf16_f32 v1, v27, s0
	v_cndmask_b32_e64 v1, v1, 0, vcc
	ds_write_b16 v2, v1 offset:39200
	s_waitcnt lgkmcnt(0)
	v_add3_u32 v1, 16, v11, v6
	ds_read_b128 v[2:5], v1 offset:17408
	ds_read_b128 v[24:27], v23 offset:37888
	s_waitcnt lgkmcnt(0)
	v_mfma_f32_16x16x32_bf16 v[24:27], v[2:5], v[24:27], 0
	v_lshlrev_b64 v[32:33], 1, v[30:31]
	v_mov_b32_e32 v1, v8
	s_nop 5
	v_cvt_pk_bf16_f32 v20, v24, v25
	v_lshlrev_b64 v[24:25], 8, v[28:29]
	v_lshl_add_u64 v[24:25], s[6:7], 0, v[24:25]
	v_lshl_add_u64 v[24:25], v[24:25], 0, v[32:33]
	v_cvt_pk_bf16_f32 v21, v26, v27
	v_lshl_add_u64 v[24:25], v[24:25], 0, v[0:1]
	global_store_dwordx2 v[24:25], v[20:21], off
	ds_read_b128 v[24:27], v23 offset:39168
	s_waitcnt lgkmcnt(0)
	v_mfma_f32_16x16x32_bf16 v[2:5], v[2:5], v[24:27], 0
	s_nop 7
	v_cvt_pk_bf16_f32 v2, v2, v3
	v_cvt_pk_bf16_f32 v3, v4, v5
	v_add_u32_e32 v4, 16, v28
	v_mov_b32_e32 v5, v8
	v_lshlrev_b64 v[4:5], 8, v[4:5]
	v_lshl_add_u64 v[4:5], s[6:7], 0, v[4:5]
	v_lshl_add_u64 v[4:5], v[4:5], 0, v[32:33]
	v_lshl_add_u64 v[4:5], v[4:5], 0, v[0:1]
	global_store_dwordx2 v[4:5], v[2:3], off
